# prefetch the next P2 work-queue index while a FoX unit runs (hides the dequeue atomic round trip)
# baseline (speedup 1.0000x reference)
.LBB0_256:
	s_cmp_lg_u32 s27, 2
	s_cselect_b64 s[0:1], -1, 0
	s_waitcnt lgkmcnt(0)
	s_xor_b64 s[54:55], s[4:5], -1
	s_and_b64 s[0:1], s[54:55], s[0:1]
	v_writelane_b32 v255, s54, 1
	s_and_b64 vcc, exec, s[0:1]
	s_nop 0
	v_writelane_b32 v255, s55, 2
	s_cbranch_vccnz .LBB0_590
	s_add_u32 s0, s76, 0x7c01000
	v_writelane_b32 v255, s0, 3
	s_addc_u32 s0, s77, 0
	v_writelane_b32 v255, s0, 4
	s_add_u32 s0, s76, 0x7c01400
	s_addc_u32 s86, s77, 0
	s_add_u32 s87, s76, 0x7c01800
	s_addc_u32 s88, s77, 0
	s_add_u32 s84, s76, 0x1e400000
	s_addc_u32 s85, s77, 0
	s_add_u32 s48, s76, 0x1dc00000
	s_addc_u32 s49, s77, 0
	s_add_u32 s50, s76, 0x23c0000
	s_addc_u32 s51, s77, 0
	s_add_u32 s89, s76, 0x2600000
	s_addc_u32 s90, s77, 0
	s_add_u32 s52, s76, 0x7c00800
	v_writelane_b32 v255, s0, 5
	s_addc_u32 s53, s77, 0
	s_add_i32 s4, 0, 0x12200
	v_mov_b32_e32 v0, 0
	v_writelane_b32 v255, s4, 6
	s_add_i32 s4, 0, 0x15500
	v_writelane_b32 v255, s4, 7
	s_add_i32 s4, 0, 0x11100
	v_mbcnt_lo_u32_b32 v0, -1, v0
	v_writelane_b32 v255, s4, 8
	s_add_i32 s4, 0, 0x13300
	v_mbcnt_hi_u32_b32 v0, -1, v0
	v_writelane_b32 v255, s4, 9
	s_add_i32 s4, 0, 0x16600
	v_add_u32_e32 v0, s33, v0
	s_add_i32 s91, 0, 0x25fc0
	v_writelane_b32 v255, s4, 10
	s_mov_b32 s58, 0x652b82fe
	s_add_i32 s4, 0, 0x14c00
	s_mov_b32 s64, 0xfff50000
	v_mov_b32_e32 v99, 0
	s_mov_b32 s55, 0
	v_cmp_eq_u32_e64 s[0:1], 0, v0
	v_mov_b32_e32 v190, s91
	s_add_i32 s92, 0, 0x1d000
	s_movk_i32 s93, 0x6ff
	s_movk_i32 s94, 0x2c00
	s_mov_b32 s95, 0x58000
	s_add_i32 s96, 0, 0x1f600
	s_add_i32 s97, 0, 0x1f400
	s_add_i32 s42, 0, 0x10000
	s_add_i32 s43, 0, 0x14400
	s_add_i32 s82, 0, 0x18800
	s_movk_i32 s28, 0x90
	s_movk_i32 s45, 0x110
	v_mov_b32_e32 v191, 0x358637bd
	s_movk_i32 s62, 0x7fff
	s_mov_b32 s63, 0x7c00000
	s_mov_b32 s44, 0x7c03000
	s_mov_b32 s59, 0x3ff71547
	s_mov_b64 s[60:61], 0x160000
	s_mov_b32 s38, 0x3f803f80
	s_mov_b64 s[80:81], 0x210000
	v_writelane_b32 v255, s4, 11
	s_mov_b32 s65, -1
	s_mov_b32 s57, 0x41000000
	v_mov_b32_e32 v196, 1.0
	v_mov_b32_e32 v197, 0xff800000
	v_mov_b32_e32 v98, 0x3f803f80
	v_mov_b32_e32 v198, 0xb0000
	s_mov_b32 s98, 0
	s_branch .LBB0_261

.LBB0_261:
	s_and_saveexec_b64 s[4:5], s[0:1]
	s_cbranch_execz .LBB0_265
	s_mov_b64 s[8:9], exec
	s_waitcnt vmcnt(23)
	v_mbcnt_lo_u32_b32 v0, s8, 0
	v_mbcnt_hi_u32_b32 v0, s9, v0
	v_cmp_eq_u32_e32 vcc, 0, v0
	s_and_saveexec_b64 s[6:7], vcc
	s_cbranch_execz .LBB0_264
	s_bcnt1_i32_b64 s8, s[8:9]
	v_mov_b32_e32 v1, s8
	s_and_b32 s100, s2, 7
	s_lshl_b32 s100, s100, 6
	s_add_i32 s100, s100, 0xb800
	s_cmp_eq_u32 s99, 0
	s_cselect_b32 s100, 0, s100
	v_mov_b32_e32 v2, s100
	s_cmp_eq_u32 s98, 1
	s_cbranch_scc1 .Lq_have
	global_atomic_add v1, v2, v1, s[76:77] sc0
	s_branch .LBB0_264
.Lq_have:
	s_waitcnt vmcnt(0)
	v_readlane_b32 s101, v255, 63
	s_nop 3
	v_mov_b32_e32 v1, s101
.LBB0_264:
	s_or_b64 exec, exec, s[6:7]
	s_waitcnt vmcnt(0)
	v_readfirstlane_b32 s6, v1
	v_mov_b32_e32 v1, s91
	s_nop 0
	v_add_u32_e32 v0, s6, v0
	ds_write_b32 v1, v0
	s_mov_b32 s98, 0
	s_cmp_eq_u32 s99, 0
	s_cbranch_scc1 .Lq_nopf
	s_cmp_lt_u32 s6, 16
	s_cbranch_scc1 .Lq_nopf
	s_cmp_lt_u32 s6, 32
	s_cbranch_scc1 .Lq_pf
	s_cmp_lt_u32 s6, 44
	s_cbranch_scc1 .Lq_nopf
	s_cmp_lt_u32 s6, 0x9c
	s_cbranch_scc0 .Lq_nopf
.Lq_pf:
	s_mov_b32 exec_lo, 0
	s_mov_b32 exec_hi, 0x80000000
	v_mov_b32_e32 v1, 1
	v_mov_b32_e32 v2, s100
	global_atomic_add v255, v2, v1, s[76:77] sc0
	s_mov_b64 exec, 1
	s_mov_b32 s98, 1
.Lq_nopf:
.LBB0_265:
	s_or_b64 exec, exec, s[4:5]
	s_waitcnt lgkmcnt(0)
	s_barrier
	s_waitcnt vmcnt(23)
	ds_read_b32 v0, v190
	s_mov_b64 s[4:5], -1
	s_waitcnt lgkmcnt(0)
	s_barrier
	v_readfirstlane_b32 s39, v0
	s_cmp_eq_u32 s99, 0
	s_cbranch_scc1 .Lq_mapped
	s_and_b32 s100, s2, 7
	s_cmp_lt_u32 s39, 12
	s_cbranch_scc0 .Lq_m1
	s_mul_i32 s101, s100, 12
	s_add_i32 s39, s39, s101
	s_branch .Lq_mapped
